# LayerNorm layer-0 path: the one-shot f32 residual loads (x / meta tokens) marked nt
# baseline (speedup 1.0000x reference)
; DI void phase_ln(const Params& p, int layer, int gw, int NGW, int lane) {
;     ...
;                 const f32x4* src32 = (const f32x4*)(rr[q] < SEQ ? p.x + (size_t)rr[q] * D : p.meta + (size_t)(rr[q] - SEQ) * D) + 2 * lane;
; #pragma unroll
;                 for (int j = 0; j < 4; ++j) { const f32x4 a0 = src32[128 * j], a1 = src32[128 * j + 1];
;                     v[q][8 * j + 0] = a0[0]; v[q][8 * j + 1] = a0[1]; v[q][8 * j + 2] = a0[2]; v[q][8 * j + 3] = a0[3];
;                     v[q][8 * j + 4] = a1[0]; v[q][8 * j + 5] = a1[1]; v[q][8 * j + 6] = a1[2]; v[q][8 * j + 7] = a1[3]; }
.LBB0_359:
	s_add_u32 s4, s34, s54
	s_addc_u32 s5, s35, s55
	s_add_i32 s6, s10, 0xffffc000
	s_cmpk_lt_i32 s10, 0x4000
	s_cselect_b32 s5, s5, 0
	s_cselect_b32 s4, s4, s6
	s_cselect_b32 s6, s73, s75
	s_cselect_b32 s7, s72, s74
	s_lshl_b64 s[4:5], s[4:5], 13
	s_add_u32 s4, s7, s4
	s_addc_u32 s5, s6, s5
	v_lshl_add_u64 v[14:15], v[104:105], 4, s[4:5]
	global_load_dwordx4 v[42:45], v[14:15], off offset:16 nt
	global_load_dwordx4 v[50:53], v[14:15], off nt
	global_load_dwordx4 v[46:49], v[14:15], off offset:2064 nt
	global_load_dwordx4 v[54:57], v[14:15], off offset:2048 nt
	v_add_co_u32_e32 v18, vcc, s62, v14
	v_lshl_add_u64 v[16:17], v[14:15], 0, s[64:65]
	s_nop 0
	v_addc_co_u32_e32 v19, vcc, 0, v15, vcc
	v_lshl_add_u64 v[20:21], v[14:15], 0, s[68:69]
	global_load_dwordx4 v[58:61], v[18:19], off nt
	global_load_dwordx4 v[22:25], v[16:17], off offset:16 nt
	s_nop 0
	global_load_dwordx4 v[14:17], v[18:19], off offset:2048 nt
	s_nop 0
	global_load_dwordx4 v[18:21], v[20:21], off offset:16 nt

; DI void phase_ln(const Params& p, int layer, int gw, int NGW, int lane) {
;     ...
;                 const f32x4* src32 = (const f32x4*)(rr[q] < SEQ ? p.x + (size_t)rr[q] * D : p.meta + (size_t)(rr[q] - SEQ) * D) + 2 * lane;
; #pragma unroll
;                 for (int j = 0; j < 4; ++j) { const f32x4 a0 = src32[128 * j], a1 = src32[128 * j + 1];
;                     v[q][8 * j + 0] = a0[0]; v[q][8 * j + 1] = a0[1]; v[q][8 * j + 2] = a0[2]; v[q][8 * j + 3] = a0[3];
;                     v[q][8 * j + 4] = a1[0]; v[q][8 * j + 5] = a1[1]; v[q][8 * j + 6] = a1[2]; v[q][8 * j + 7] = a1[3]; }
.LBB0_362:
	s_add_i32 s6, s56, 0xffffc000
	s_cmpk_lt_i32 s56, 0x4000
	s_cselect_b32 s7, s57, 0
	s_cselect_b32 s6, s56, s6
	s_cselect_b32 s11, s73, s75
	s_cselect_b32 s23, s72, s74
	s_lshl_b64 s[6:7], s[6:7], 13
	s_add_u32 s6, s23, s6
	s_addc_u32 s7, s11, s7
	v_lshl_add_u64 v[66:67], v[104:105], 4, s[6:7]
	global_load_dwordx4 v[82:85], v[66:67], off offset:16 nt
	global_load_dwordx4 v[94:97], v[66:67], off nt
	global_load_dwordx4 v[70:73], v[66:67], off offset:2064 nt
	global_load_dwordx4 v[90:93], v[66:67], off offset:2048 nt
	v_add_co_u32_e32 v74, vcc, s62, v66
	v_lshl_add_u64 v[68:69], v[66:67], 0, s[64:65]
	s_nop 0
	v_addc_co_u32_e32 v75, vcc, 0, v67, vcc
	v_lshl_add_u64 v[66:67], v[66:67], 0, s[68:69]
	global_load_dwordx4 v[86:89], v[74:75], off nt
	global_load_dwordx4 v[78:81], v[68:69], off offset:16 nt
	s_nop 0
	global_load_dwordx4 v[74:77], v[74:75], off offset:2048 nt
	s_nop 0
	global_load_dwordx4 v[66:69], v[66:67], off offset:16 nt
